# baseline (speedup 1.0000x reference)
; #define HG_ISSUE(c) do { const int p_ = (c) * 32 + lt; const int tok_ = tokbase + (dir ? 511 - p_ : p_); const u16* rp_ = PROJ + (size_t)tok_ * INP + h * 128 + lc; \
;     rq = ld8(rp_ + C_HQ); rf = ld8(rp_ + fcol); rv = ld8(rp_ + C_HI); } while (0)
; #define HG_ISSUE(c) do { const int p_ = (c) * 64 + lt; const int tok_ = tokbase + (dir ? 511 - p_ : p_); const u16* rp_ = PROJ + (size_t)tok_ * INP + h * 128 + lc; \
;     if (MODE == 1) { rq0 = ld8(rp_ + C_HQ); rq1 = ld8(rp_ + C_HQ + 8); } rf0 = ld8(rp_ + fcol); rf1 = ld8(rp_ + fcol + 8); rv0 = ld8(rp_ + C_HI); rv1 = ld8(rp_ + C_HI + 8); } while (0)
; template <int MODE>
; DI void hgrn_item2(const u16* PROJ, int tokbase, int dir, int h, int layer, const float* hgrn_lb, float* Sg, float* Pg,
;                    u16* OH, const float* norm_g, char* lds) {
;     ...
;     if (MODE == 1) { *reinterpret_cast<bf16x8*>(lds + HL_RAWQ + lt * 256 + lc * 2) = rq0; *reinterpret_cast<bf16x8*>(lds + HL_RAWQ + lt * 256 + lc * 2 + 16) = rq1; }
;     *reinterpret_cast<bf16x8*>(lds + HL_RAWF + lt * 256 + lc * 2) = rf0; *reinterpret_cast<bf16x8*>(lds + HL_RAWF + lt * 256 + lc * 2 + 16) = rf1;
;     { const int vsw = ((((lt >> 3) ^ (tid & 7)) * 8) + (lt & 7)) * 2;
; #pragma unroll
;       for (int j = 0; j < 8; ++j) { *reinterpret_cast<short*>(lds + HL_VT + (lc + j) * 144 + vsw) = rv0[j]; *reinterpret_cast<short*>(lds + HL_VT + (lc + 8 + j) * 144 + vsw) = rv1[j]; } }
;     if (c + 1 < 8) HG_ISSUE(c + 1);
.LBB0_67:
	s_cmpk_eq_i32 s90, 0xfe40
	s_waitcnt vmcnt(9)
	ds_write_b128 v96, v[48:51]
	s_waitcnt vmcnt(8)
	ds_write_b128 v96, v[52:55] offset:16
	s_waitcnt vmcnt(7)
	ds_write_b128 v96, v[56:59] offset:16384
	s_waitcnt vmcnt(6)
	ds_write_b128 v96, v[60:63] offset:16400
	s_waitcnt vmcnt(5)
	ds_write_b16 v144, v64 offset:32768
	s_waitcnt vmcnt(4)
	ds_write_b16 v144, v68 offset:33920
	ds_write_b16_d16_hi v144, v64 offset:32912
	ds_write_b16_d16_hi v144, v68 offset:34064
	ds_write_b16 v144, v65 offset:33056
	ds_write_b16 v144, v69 offset:34208
	ds_write_b16_d16_hi v144, v65 offset:33200
	ds_write_b16_d16_hi v144, v69 offset:34352
	ds_write_b16 v144, v66 offset:33344
	ds_write_b16 v144, v70 offset:34496
	ds_write_b16_d16_hi v144, v66 offset:33488
	ds_write_b16_d16_hi v144, v70 offset:34640
	ds_write_b16 v144, v67 offset:33632
	ds_write_b16 v144, v71 offset:34784
	ds_write_b16_d16_hi v144, v67 offset:33776
	ds_write_b16_d16_hi v144, v71 offset:34928
	s_cbranch_scc1 .LBB0_69
	v_add_u32_e32 v0, s90, v143
	v_cndmask_b32_e64 v0, v0, v142, s[98:99]
	v_add_u32_e32 v0, s88, v0
	v_mad_i64_i32 v[0:1], s[6:7], v0, s33, v[88:89]
	global_load_dwordx4 v[48:51], v[0:1], off
	global_load_dwordx4 v[52:55], v[0:1], off offset:16
	v_lshl_add_u64 v[2:3], v[0:1], 0, s[84:85]
	v_add_co_u32_e32 v0, vcc, 0x1000, v0
	global_load_dwordx4 v[56:59], v[2:3], off
	global_load_dwordx4 v[60:63], v[2:3], off offset:16
	v_addc_co_u32_e32 v1, vcc, 0, v1, vcc
	global_load_dwordx4 v[64:67], v[0:1], off offset:2048
	global_load_dwordx4 v[68:71], v[0:1], off offset:2064
